# attention key loop hand-rescheduled: fragment ds_reads software-pipelined one MFMA segment ahead, PV second half rotated across the barrier
# speedup vs baseline: 1.0313x; 1.0313x over previous
.Latt_A_rare1:
	v_max_f32_e32 v244, v243, v243
	v_max_f32_e32 v245, 0, v244
	v_exp_f32_e64 v244, -v245
	v_add_f32_e32 v237, v237, v245
	v_xor_b32_e32 v82, 0x80000000, v237
	v_mul_f32_e32 v238, v238, v244
	v_sub_f32_e32 v98, v98, v245
	v_sub_f32_e32 v99, v99, v245
	v_sub_f32_e32 v100, v100, v245
	v_sub_f32_e32 v101, v101, v245
	v_sub_f32_e32 v102, v102, v245
	v_sub_f32_e32 v103, v103, v245
	v_sub_f32_e32 v104, v104, v245
	v_sub_f32_e32 v105, v105, v245
	v_sub_f32_e32 v106, v106, v245
	v_sub_f32_e32 v107, v107, v245
	v_sub_f32_e32 v108, v108, v245
	v_sub_f32_e32 v109, v109, v245
	v_sub_f32_e32 v110, v110, v245
	v_sub_f32_e32 v111, v111, v245
	v_sub_f32_e32 v112, v112, v245
	v_sub_f32_e32 v113, v113, v245
	v_sub_f32_e32 v66, v66, v245
	v_sub_f32_e32 v67, v67, v245
	v_sub_f32_e32 v68, v68, v245
	v_sub_f32_e32 v69, v69, v245
	v_sub_f32_e32 v70, v70, v245
	v_sub_f32_e32 v71, v71, v245
	v_sub_f32_e32 v72, v72, v245
	v_sub_f32_e32 v73, v73, v245
	v_sub_f32_e32 v74, v74, v245
	v_sub_f32_e32 v75, v75, v245
	v_sub_f32_e32 v76, v76, v245
	v_sub_f32_e32 v77, v77, v245
	v_sub_f32_e32 v78, v78, v245
	v_sub_f32_e32 v79, v79, v245
	v_sub_f32_e32 v80, v80, v245
	v_sub_f32_e32 v81, v81, v245
	v_mov_b32_e32 v83, v82
	v_mov_b32_e32 v84, v82
	v_mov_b32_e32 v85, v82
	v_mov_b32_e32 v86, v82
	v_mov_b32_e32 v87, v82
	v_mov_b32_e32 v88, v82
	v_mov_b32_e32 v89, v82
	v_mov_b32_e32 v90, v82
	v_mov_b32_e32 v91, v82
	v_mov_b32_e32 v92, v82
	v_mov_b32_e32 v93, v82
	v_mov_b32_e32 v94, v82
	v_mov_b32_e32 v95, v82
	v_mov_b32_e32 v96, v82
	v_mov_b32_e32 v97, v82
	s_branch .Latt_A_dma
.Latt_A_rare2:
	s_nop 15
	v_pk_mul_f32 v[2:3], v[2:3], v[244:245] op_sel_hi:[1,0]
	v_pk_mul_f32 v[4:5], v[4:5], v[244:245] op_sel_hi:[1,0]
	v_pk_mul_f32 v[6:7], v[6:7], v[244:245] op_sel_hi:[1,0]
	v_pk_mul_f32 v[8:9], v[8:9], v[244:245] op_sel_hi:[1,0]
	v_pk_mul_f32 v[10:11], v[10:11], v[244:245] op_sel_hi:[1,0]
	v_pk_mul_f32 v[12:13], v[12:13], v[244:245] op_sel_hi:[1,0]
	v_pk_mul_f32 v[14:15], v[14:15], v[244:245] op_sel_hi:[1,0]
	v_pk_mul_f32 v[16:17], v[16:17], v[244:245] op_sel_hi:[1,0]
	v_pk_mul_f32 v[50:51], v[50:51], v[244:245] op_sel_hi:[1,0]
	v_pk_mul_f32 v[52:53], v[52:53], v[244:245] op_sel_hi:[1,0]
	v_pk_mul_f32 v[54:55], v[54:55], v[244:245] op_sel_hi:[1,0]
	v_pk_mul_f32 v[56:57], v[56:57], v[244:245] op_sel_hi:[1,0]
	v_pk_mul_f32 v[58:59], v[58:59], v[244:245] op_sel_hi:[1,0]
	v_pk_mul_f32 v[60:61], v[60:61], v[244:245] op_sel_hi:[1,0]
	v_pk_mul_f32 v[62:63], v[62:63], v[244:245] op_sel_hi:[1,0]
	v_pk_mul_f32 v[64:65], v[64:65], v[244:245] op_sel_hi:[1,0]
	v_pk_mul_f32 v[34:35], v[34:35], v[244:245] op_sel_hi:[1,0]
	v_pk_mul_f32 v[36:37], v[36:37], v[244:245] op_sel_hi:[1,0]
	v_pk_mul_f32 v[38:39], v[38:39], v[244:245] op_sel_hi:[1,0]
	v_pk_mul_f32 v[40:41], v[40:41], v[244:245] op_sel_hi:[1,0]
	v_pk_mul_f32 v[42:43], v[42:43], v[244:245] op_sel_hi:[1,0]
	v_pk_mul_f32 v[44:45], v[44:45], v[244:245] op_sel_hi:[1,0]
	v_pk_mul_f32 v[46:47], v[46:47], v[244:245] op_sel_hi:[1,0]
	v_pk_mul_f32 v[48:49], v[48:49], v[244:245] op_sel_hi:[1,0]
	v_pk_mul_f32 v[18:19], v[18:19], v[244:245] op_sel_hi:[1,0]
	v_pk_mul_f32 v[20:21], v[20:21], v[244:245] op_sel_hi:[1,0]
	v_pk_mul_f32 v[22:23], v[22:23], v[244:245] op_sel_hi:[1,0]
	v_pk_mul_f32 v[24:25], v[24:25], v[244:245] op_sel_hi:[1,0]
	v_pk_mul_f32 v[26:27], v[26:27], v[244:245] op_sel_hi:[1,0]
	v_pk_mul_f32 v[28:29], v[28:29], v[244:245] op_sel_hi:[1,0]
	v_pk_mul_f32 v[30:31], v[30:31], v[244:245] op_sel_hi:[1,0]
	v_pk_mul_f32 v[32:33], v[32:33], v[244:245] op_sel_hi:[1,0]
	s_nop 1
	s_branch .Latt_A_segD
.Latt_B_rare1:
	v_max_f32_e32 v244, v246, v246
	v_max_f32_e32 v245, 0, v244
	v_exp_f32_e64 v244, -v245
	v_add_f32_e32 v237, v237, v245
	v_xor_b32_e32 v82, 0x80000000, v237
	v_mul_f32_e32 v238, v238, v244
	v_sub_f32_e32 v146, v146, v245
	v_sub_f32_e32 v147, v147, v245
	v_sub_f32_e32 v148, v148, v245
	v_sub_f32_e32 v149, v149, v245
	v_sub_f32_e32 v150, v150, v245
	v_sub_f32_e32 v151, v151, v245
	v_sub_f32_e32 v152, v152, v245
	v_sub_f32_e32 v153, v153, v245
	v_sub_f32_e32 v154, v154, v245
	v_sub_f32_e32 v155, v155, v245
	v_sub_f32_e32 v156, v156, v245
	v_sub_f32_e32 v157, v157, v245
	v_sub_f32_e32 v158, v158, v245
	v_sub_f32_e32 v159, v159, v245
	v_sub_f32_e32 v160, v160, v245
	v_sub_f32_e32 v161, v161, v245
	v_sub_f32_e32 v114, v114, v245
	v_sub_f32_e32 v115, v115, v245
	v_sub_f32_e32 v116, v116, v245
	v_sub_f32_e32 v117, v117, v245
	v_sub_f32_e32 v118, v118, v245
	v_sub_f32_e32 v119, v119, v245
	v_sub_f32_e32 v120, v120, v245
	v_sub_f32_e32 v121, v121, v245
	v_sub_f32_e32 v122, v122, v245
	v_sub_f32_e32 v123, v123, v245
	v_sub_f32_e32 v124, v124, v245
	v_sub_f32_e32 v125, v125, v245
	v_sub_f32_e32 v126, v126, v245
	v_sub_f32_e32 v127, v127, v245
	v_sub_f32_e32 v128, v128, v245
	v_sub_f32_e32 v129, v129, v245
	v_mov_b32_e32 v83, v82
	v_mov_b32_e32 v84, v82
	v_mov_b32_e32 v85, v82
	v_mov_b32_e32 v86, v82
	v_mov_b32_e32 v87, v82
	v_mov_b32_e32 v88, v82
	v_mov_b32_e32 v89, v82
	v_mov_b32_e32 v90, v82
	v_mov_b32_e32 v91, v82
	v_mov_b32_e32 v92, v82
	v_mov_b32_e32 v93, v82
	v_mov_b32_e32 v94, v82
	v_mov_b32_e32 v95, v82
	v_mov_b32_e32 v96, v82
	v_mov_b32_e32 v97, v82
	s_branch .Latt_B_dma

.Latt_entry:
	v_mov_b32_e32 v243, 0
	v_add_u32_e32 v239, v228, v229
	v_add_u32_e32 v240, v228, v231
	v_add_u32_e32 v241, v228, v233
	v_add_u32_e32 v242, v228, v235
	s_add_i32 s4, s22, -1
	s_cmp_lt_u32 s4, s21
	s_cselect_b64 s[2:3], -1, 0
	s_cmp_ge_u32 s4, s21
	v_lshl_add_u64 v[186:187], v[180:181], 0, s[0:1]
	s_cbranch_scc1 .Latt_E_noK
	s_mov_b64 s[6:7], 0xea0c000
	v_lshl_add_u64 v[192:193], v[186:187], 0, s[6:7]
	s_mov_b64 s[6:7], 0xe804000
	v_readfirstlane_b32 s5, v0
	v_lshl_add_u64 v[194:195], v[186:187], 0, s[6:7]
	s_mov_b32 m0, s5
	v_readfirstlane_b32 s5, v223
	global_load_lds_dwordx4 v[194:195], off
	s_mov_b32 m0, s5
	s_nop 0
	global_load_lds_dwordx4 v[192:193], off
.Latt_E_noK:
	s_add_i32 s5, s22, -2
	s_cmp_ge_u32 s5, s21
	v_lshl_add_u64 v[190:191], v[182:183], 0, s[0:1]
	v_lshl_add_u64 v[188:189], v[184:185], 0, s[0:1]
	s_cbranch_scc1 .Latt_E_noV
	v_add_u32_e32 v192, 0xc000, v0
	s_mov_b64 s[6:7], 0x10880080
	v_lshl_add_u64 v[194:195], v[188:189], 0, s[6:7]
	v_readfirstlane_b32 s5, v192
	s_mov_b32 m0, s5
	v_lshl_add_u64 v[192:193], v[190:191], 0, s[6:7]
	global_load_lds_dwordx4 v[194:195], off
	v_add_u32_e32 v194, 0xe000, v0
	s_nop 0
	v_readfirstlane_b32 s5, v194
	s_mov_b32 m0, s5
	s_nop 0
	global_load_lds_dwordx4 v[192:193], off
.Latt_E_noV:
	ds_read_b128 v[130:133], v230 offset:16384
	v_exp_f32_e32 v98, v98
	v_exp_f32_e32 v99, v99
	v_add_f32_e32 v247, 0, v98
	v_add_f32_e32 v247, v99, v247
	ds_read_b128 v[134:137], v230 offset:20480
	v_exp_f32_e32 v100, v100
	v_exp_f32_e32 v101, v101
	v_add_f32_e32 v247, v100, v247
	v_add_f32_e32 v247, v101, v247
	ds_read_b128 v[138:141], v232 offset:16384
	v_exp_f32_e32 v102, v102
	v_exp_f32_e32 v103, v103
	v_add_f32_e32 v247, v102, v247
	v_add_f32_e32 v247, v103, v247
	ds_read_b128 v[142:145], v232 offset:20480
	v_exp_f32_e32 v104, v104
	v_exp_f32_e32 v105, v105
	v_add_f32_e32 v247, v104, v247
	v_add_f32_e32 v247, v105, v247
	ds_read_b128 v[200:203], v234 offset:16384
	v_exp_f32_e32 v106, v106
	v_exp_f32_e32 v107, v107
	v_add_f32_e32 v247, v106, v247
	v_add_f32_e32 v247, v107, v247
	ds_read_b128 v[204:207], v234 offset:20480
	v_exp_f32_e32 v108, v108
	v_exp_f32_e32 v109, v109
	v_add_f32_e32 v247, v108, v247
	v_add_f32_e32 v247, v109, v247
	ds_read_b128 v[208:211], v236 offset:16384
	v_exp_f32_e32 v110, v110
	v_exp_f32_e32 v111, v111
	v_add_f32_e32 v247, v110, v247
	v_add_f32_e32 v247, v111, v247
	ds_read_b128 v[212:215], v236 offset:20480
	v_exp_f32_e32 v112, v112
	v_exp_f32_e32 v113, v113
	v_add_f32_e32 v247, v112, v247
	v_add_f32_e32 v247, v113, v247
	s_branch .Latt_A_segD
.LBB0_1097:
	v_cmp_lt_f32_e32 vcc, s26, v243
	s_cbranch_vccnz .Latt_A_rare1
.Latt_A_dma:
	s_add_i32 s4, s22, -1
	s_cmp_lt_u32 s4, s21
	s_cselect_b64 s[2:3], -1, 0
	s_cmp_ge_u32 s4, s21
	v_lshl_add_u64 v[186:187], v[180:181], 0, s[0:1]
	s_cbranch_scc1 .Latt_A_noK
	s_mov_b64 s[6:7], 0xea0c000
	v_lshl_add_u64 v[192:193], v[186:187], 0, s[6:7]
	s_mov_b64 s[6:7], 0xe804000
	v_readfirstlane_b32 s5, v0
	v_lshl_add_u64 v[194:195], v[186:187], 0, s[6:7]
	s_mov_b32 m0, s5
	v_readfirstlane_b32 s5, v223
	global_load_lds_dwordx4 v[194:195], off
	s_mov_b32 m0, s5
	s_nop 0
	global_load_lds_dwordx4 v[192:193], off

.Latt_A_noV:
	v_mfma_f32_32x32x16_bf16 v[2:17], v[130:133], v[114:117], v[2:17]
	ds_read_b128 v[130:133], v230 offset:16384
	v_exp_f32_e32 v98, v98
	v_exp_f32_e32 v99, v99
	v_add_f32_e32 v247, 0, v98
	v_add_f32_e32 v247, v99, v247
	v_mfma_f32_32x32x16_bf16 v[50:65], v[134:137], v[114:117], v[50:65]
	ds_read_b128 v[134:137], v230 offset:20480
	v_exp_f32_e32 v100, v100
	v_exp_f32_e32 v101, v101
	v_add_f32_e32 v247, v100, v247
	v_add_f32_e32 v247, v101, v247
	v_mfma_f32_32x32x16_bf16 v[34:49], v[138:141], v[114:117], v[34:49]
	ds_read_b128 v[138:141], v232 offset:16384
	v_exp_f32_e32 v102, v102
	v_exp_f32_e32 v103, v103
	v_add_f32_e32 v247, v102, v247
	v_add_f32_e32 v247, v103, v247
	v_mfma_f32_32x32x16_bf16 v[18:33], v[142:145], v[114:117], v[18:33]
	ds_read_b128 v[142:145], v232 offset:20480
	v_exp_f32_e32 v104, v104
	v_exp_f32_e32 v105, v105
	v_add_f32_e32 v247, v104, v247
	v_add_f32_e32 v247, v105, v247
	v_mfma_f32_32x32x16_bf16 v[2:17], v[200:203], v[118:121], v[2:17]
	ds_read_b128 v[200:203], v234 offset:16384
	v_exp_f32_e32 v106, v106
	v_exp_f32_e32 v107, v107
	v_add_f32_e32 v247, v106, v247
	v_add_f32_e32 v247, v107, v247
	v_mfma_f32_32x32x16_bf16 v[50:65], v[204:207], v[118:121], v[50:65]
	ds_read_b128 v[204:207], v234 offset:20480
	v_exp_f32_e32 v108, v108
	v_exp_f32_e32 v109, v109
	v_add_f32_e32 v247, v108, v247
	v_add_f32_e32 v247, v109, v247
	v_mfma_f32_32x32x16_bf16 v[34:49], v[208:211], v[118:121], v[34:49]
	ds_read_b128 v[208:211], v236 offset:16384
	v_exp_f32_e32 v110, v110
	v_exp_f32_e32 v111, v111
	v_add_f32_e32 v247, v110, v247
	v_add_f32_e32 v247, v111, v247
	v_mfma_f32_32x32x16_bf16 v[18:33], v[212:215], v[118:121], v[18:33]
	ds_read_b128 v[212:215], v236 offset:20480
	v_exp_f32_e32 v112, v112
	v_exp_f32_e32 v113, v113
	v_add_f32_e32 v247, v112, v247
	v_add_f32_e32 v247, v113, v247
	v_cmp_lt_f32_e32 vcc, s26, v243
	s_cbranch_vccnz .Latt_A_rare2
.Latt_A_segD:
	s_waitcnt lgkmcnt(7)
	v_mfma_f32_32x32x16_bf16 v[146:161], v[130:133], v[162:165], v[82:97]
	ds_read_b128 v[130:133], v239 offset:32768
	v_exp_f32_e32 v66, v66
	v_cvt_pk_bf16_f32 v98, v98, v99
	v_add_f32_e32 v247, v66, v247
	s_waitcnt lgkmcnt(7)
	v_mfma_f32_32x32x16_bf16 v[114:129], v[134:137], v[162:165], v[82:97]
	ds_read_b128 v[134:137], v239 offset:36864
	v_exp_f32_e32 v67, v67
	v_cvt_pk_bf16_f32 v99, v100, v101
	v_add_f32_e32 v247, v67, v247
	s_waitcnt lgkmcnt(7)
	v_mfma_f32_32x32x16_bf16 v[146:161], v[138:141], v[166:169], v[146:161]
	ds_read_b128 v[138:141], v239 offset:40960
	v_exp_f32_e32 v68, v68
	v_cvt_pk_bf16_f32 v100, v102, v103
	v_add_f32_e32 v247, v68, v247
	s_waitcnt lgkmcnt(7)
	v_mfma_f32_32x32x16_bf16 v[114:129], v[142:145], v[166:169], v[114:129]
	ds_read_b128 v[142:145], v239 offset:45056
	v_exp_f32_e32 v69, v69
	v_cvt_pk_bf16_f32 v101, v104, v105
	v_add_f32_e32 v247, v69, v247
	s_waitcnt lgkmcnt(7)
	v_mfma_f32_32x32x16_bf16 v[146:161], v[200:203], v[170:173], v[146:161]
	ds_read_b128 v[200:203], v240 offset:32768
	v_exp_f32_e32 v70, v70
	v_cvt_pk_bf16_f32 v102, v106, v107
	v_add_f32_e32 v247, v70, v247
	s_waitcnt lgkmcnt(7)
	v_mfma_f32_32x32x16_bf16 v[114:129], v[204:207], v[170:173], v[114:129]
	ds_read_b128 v[204:207], v240 offset:36864
	v_exp_f32_e32 v71, v71
	v_cvt_pk_bf16_f32 v103, v108, v109
	v_add_f32_e32 v247, v71, v247
	s_waitcnt lgkmcnt(7)
	v_mfma_f32_32x32x16_bf16 v[146:161], v[208:211], v[174:177], v[146:161]
	ds_read_b128 v[208:211], v240 offset:40960
	v_exp_f32_e32 v72, v72
	v_cvt_pk_bf16_f32 v104, v110, v111
	v_add_f32_e32 v247, v72, v247
	s_waitcnt lgkmcnt(7)
	v_mfma_f32_32x32x16_bf16 v[114:129], v[212:215], v[174:177], v[114:129]
	ds_read_b128 v[212:215], v240 offset:45056
	v_exp_f32_e32 v73, v73
	v_cvt_pk_bf16_f32 v105, v112, v113
	v_add_f32_e32 v247, v73, v247
	s_waitcnt lgkmcnt(7)
	v_mfma_f32_32x32x16_bf16 v[2:17], v[130:133], v[98:101], v[2:17]
	ds_read_b128 v[130:133], v241 offset:32768
	v_exp_f32_e32 v74, v74
	v_exp_f32_e32 v75, v75
	v_add_f32_e32 v247, v74, v247
	v_add_f32_e32 v247, v75, v247
	s_waitcnt lgkmcnt(7)
	v_mfma_f32_32x32x16_bf16 v[50:65], v[134:137], v[98:101], v[50:65]
	ds_read_b128 v[134:137], v241 offset:36864
	v_exp_f32_e32 v76, v76
	v_exp_f32_e32 v77, v77
	v_add_f32_e32 v247, v76, v247
	v_add_f32_e32 v247, v77, v247
	s_waitcnt lgkmcnt(7)
	v_mfma_f32_32x32x16_bf16 v[34:49], v[138:141], v[98:101], v[34:49]
	ds_read_b128 v[138:141], v241 offset:40960
	v_exp_f32_e32 v78, v78
	v_exp_f32_e32 v79, v79
	v_add_f32_e32 v247, v78, v247
	v_add_f32_e32 v247, v79, v247
	s_waitcnt lgkmcnt(7)
	v_mfma_f32_32x32x16_bf16 v[18:33], v[142:145], v[98:101], v[18:33]
	ds_read_b128 v[142:145], v241 offset:45056
	v_exp_f32_e32 v80, v80
	v_exp_f32_e32 v81, v81
	v_add_f32_e32 v247, v80, v247
	v_add_f32_e32 v247, v81, v247
	s_waitcnt lgkmcnt(7)
	v_mfma_f32_32x32x16_bf16 v[2:17], v[200:203], v[102:105], v[2:17]
	ds_read_b128 v[200:203], v242 offset:32768
	v_cvt_pk_bf16_f32 v66, v66, v67
	v_cvt_pk_bf16_f32 v67, v68, v69
	s_waitcnt lgkmcnt(7)
	v_mfma_f32_32x32x16_bf16 v[50:65], v[204:207], v[102:105], v[50:65]
	ds_read_b128 v[204:207], v242 offset:36864
	v_cvt_pk_bf16_f32 v68, v70, v71
	v_cvt_pk_bf16_f32 v69, v72, v73
	s_waitcnt lgkmcnt(7)
	v_mfma_f32_32x32x16_bf16 v[34:49], v[208:211], v[102:105], v[34:49]
	ds_read_b128 v[208:211], v242 offset:40960
	v_cvt_pk_bf16_f32 v70, v74, v75
	v_cvt_pk_bf16_f32 v71, v76, v77
	s_waitcnt lgkmcnt(7)
	v_mfma_f32_32x32x16_bf16 v[18:33], v[212:215], v[102:105], v[18:33]
	ds_read_b128 v[212:215], v242 offset:45056
	v_cvt_pk_bf16_f32 v72, v78, v79
	v_cvt_pk_bf16_f32 v73, v80, v81
	v_add_f32_e32 v238, v238, v247
	v_max_i32_e32 v192, v146, v114
	ds_bpermute_b32 v193, v222, v192
	s_waitcnt vmcnt(0) lgkmcnt(0)
	v_max_i32_e32 v246, v192, v193
	s_barrier
	v_cmp_lt_f32_e32 vcc, s26, v246
	s_cbranch_vccnz .Latt_B_rare1
.Latt_B_dma:
	s_cmp_ge_u32 s22, s21
	s_cbranch_scc1 .Latt_B_noK
	s_mov_b64 s[6:7], 0xe806000
	v_readfirstlane_b32 s5, v226
	v_lshl_add_u64 v[192:193], v[186:187], 0, s[6:7]
	s_mov_b64 s[6:7], 0xea0e000
	s_mov_b32 m0, s5
	v_readfirstlane_b32 s5, v227
	v_lshl_add_u64 v[194:195], v[186:187], 0, s[6:7]
	global_load_lds_dwordx4 v[192:193], off
	s_mov_b32 m0, s5
	s_nop 0
	global_load_lds_dwordx4 v[194:195], off
.Latt_B_noK:
	s_andn2_b64 vcc, exec, s[2:3]
	s_cbranch_vccnz .Latt_B_noV
	s_mov_b64 s[2:3], 0x10880100
	v_lshl_add_u64 v[192:193], v[190:191], 0, s[2:3]
	v_lshl_add_u64 v[194:195], v[188:189], 0, s[2:3]
	v_readfirstlane_b32 s2, v224
	s_mov_b32 m0, s2
	v_readfirstlane_b32 s2, v225
	global_load_lds_dwordx4 v[194:195], off
	s_mov_b32 m0, s2
	s_nop 0
	global_load_lds_dwordx4 v[192:193], off
.Latt_B_noV:
	v_mfma_f32_32x32x16_bf16 v[2:17], v[130:133], v[66:69], v[2:17]
	ds_read_b128 v[130:133], v230 offset:0
	v_exp_f32_e32 v146, v146
	v_exp_f32_e32 v147, v147
	v_add_f32_e32 v247, 0, v146
	v_add_f32_e32 v247, v147, v247
	v_mfma_f32_32x32x16_bf16 v[50:65], v[134:137], v[66:69], v[50:65]
	ds_read_b128 v[134:137], v230 offset:4096
	v_exp_f32_e32 v148, v148
	v_exp_f32_e32 v149, v149
	v_add_f32_e32 v247, v148, v247
	v_add_f32_e32 v247, v149, v247
	v_mfma_f32_32x32x16_bf16 v[34:49], v[138:141], v[66:69], v[34:49]
	ds_read_b128 v[138:141], v232 offset:0
	v_exp_f32_e32 v150, v150
	v_exp_f32_e32 v151, v151
	v_add_f32_e32 v247, v150, v247
	v_add_f32_e32 v247, v151, v247
	v_mfma_f32_32x32x16_bf16 v[18:33], v[142:145], v[66:69], v[18:33]
	ds_read_b128 v[142:145], v232 offset:4096
	v_exp_f32_e32 v152, v152
	v_exp_f32_e32 v153, v153
	v_add_f32_e32 v247, v152, v247
	v_add_f32_e32 v247, v153, v247
	v_mfma_f32_32x32x16_bf16 v[2:17], v[200:203], v[70:73], v[2:17]
	ds_read_b128 v[200:203], v234 offset:0
	v_exp_f32_e32 v154, v154
	v_exp_f32_e32 v155, v155
	v_add_f32_e32 v247, v154, v247
	v_add_f32_e32 v247, v155, v247
	v_mfma_f32_32x32x16_bf16 v[50:65], v[204:207], v[70:73], v[50:65]
	ds_read_b128 v[204:207], v234 offset:4096
	v_exp_f32_e32 v156, v156
	v_exp_f32_e32 v157, v157
	v_add_f32_e32 v247, v156, v247
	v_add_f32_e32 v247, v157, v247
	v_mfma_f32_32x32x16_bf16 v[34:49], v[208:211], v[70:73], v[34:49]
	ds_read_b128 v[208:211], v236 offset:0
	v_exp_f32_e32 v158, v158
	v_exp_f32_e32 v159, v159
	v_add_f32_e32 v247, v158, v247
	v_add_f32_e32 v247, v159, v247
	v_mfma_f32_32x32x16_bf16 v[18:33], v[212:215], v[70:73], v[18:33]
	ds_read_b128 v[212:215], v236 offset:4096
	v_exp_f32_e32 v160, v160
	v_exp_f32_e32 v161, v161
	v_add_f32_e32 v247, v160, v247
	v_add_f32_e32 v247, v161, v247
	v_cmp_lt_f32_e32 vcc, s26, v246
	s_cbranch_vccnz .Latt_B_rare2
.Latt_B_segD:
	s_waitcnt lgkmcnt(7)
	v_mfma_f32_32x32x16_bf16 v[98:113], v[130:133], v[162:165], v[82:97]
	ds_read_b128 v[130:133], v239 offset:49152
	v_exp_f32_e32 v114, v114
	v_cvt_pk_bf16_f32 v146, v146, v147
	v_add_f32_e32 v247, v114, v247
	s_waitcnt lgkmcnt(7)
	v_mfma_f32_32x32x16_bf16 v[66:81], v[134:137], v[162:165], v[82:97]
	ds_read_b128 v[134:137], v239 offset:53248
	v_exp_f32_e32 v115, v115
	v_cvt_pk_bf16_f32 v147, v148, v149
	v_add_f32_e32 v247, v115, v247
	s_waitcnt lgkmcnt(7)
	v_mfma_f32_32x32x16_bf16 v[98:113], v[138:141], v[166:169], v[98:113]
	ds_read_b128 v[138:141], v239 offset:57344
	v_exp_f32_e32 v116, v116
	v_cvt_pk_bf16_f32 v148, v150, v151
	v_add_f32_e32 v247, v116, v247
	s_waitcnt lgkmcnt(7)
	v_mfma_f32_32x32x16_bf16 v[66:81], v[142:145], v[166:169], v[66:81]
	ds_read_b128 v[142:145], v239 offset:61440
	v_exp_f32_e32 v117, v117
	v_cvt_pk_bf16_f32 v149, v152, v153
	v_add_f32_e32 v247, v117, v247
	s_waitcnt lgkmcnt(7)
	v_mfma_f32_32x32x16_bf16 v[98:113], v[200:203], v[170:173], v[98:113]
	ds_read_b128 v[200:203], v240 offset:49152
	v_exp_f32_e32 v118, v118
	v_cvt_pk_bf16_f32 v150, v154, v155
	v_add_f32_e32 v247, v118, v247
	s_waitcnt lgkmcnt(7)
	v_mfma_f32_32x32x16_bf16 v[66:81], v[204:207], v[170:173], v[66:81]
	ds_read_b128 v[204:207], v240 offset:53248
	v_exp_f32_e32 v119, v119
	v_cvt_pk_bf16_f32 v151, v156, v157
	v_add_f32_e32 v247, v119, v247
	s_waitcnt lgkmcnt(7)
	v_mfma_f32_32x32x16_bf16 v[98:113], v[208:211], v[174:177], v[98:113]
	ds_read_b128 v[208:211], v240 offset:57344
	v_exp_f32_e32 v120, v120
	v_cvt_pk_bf16_f32 v152, v158, v159
	v_add_f32_e32 v247, v120, v247
	s_waitcnt lgkmcnt(7)
	v_mfma_f32_32x32x16_bf16 v[66:81], v[212:215], v[174:177], v[66:81]
	ds_read_b128 v[212:215], v240 offset:61440
	v_exp_f32_e32 v121, v121
	v_cvt_pk_bf16_f32 v153, v160, v161
	v_add_f32_e32 v247, v121, v247
	s_waitcnt lgkmcnt(7)
	v_mfma_f32_32x32x16_bf16 v[2:17], v[130:133], v[146:149], v[2:17]
	ds_read_b128 v[130:133], v241 offset:49152
	v_exp_f32_e32 v122, v122
	v_exp_f32_e32 v123, v123
	v_add_f32_e32 v247, v122, v247
	v_add_f32_e32 v247, v123, v247
	s_waitcnt lgkmcnt(7)
	v_mfma_f32_32x32x16_bf16 v[50:65], v[134:137], v[146:149], v[50:65]
	ds_read_b128 v[134:137], v241 offset:53248
	v_exp_f32_e32 v124, v124
	v_exp_f32_e32 v125, v125
	v_add_f32_e32 v247, v124, v247
	v_add_f32_e32 v247, v125, v247
	s_waitcnt lgkmcnt(7)
	v_mfma_f32_32x32x16_bf16 v[34:49], v[138:141], v[146:149], v[34:49]
	ds_read_b128 v[138:141], v241 offset:57344
	v_exp_f32_e32 v126, v126
	v_exp_f32_e32 v127, v127
	v_add_f32_e32 v247, v126, v247
	v_add_f32_e32 v247, v127, v247
	s_waitcnt lgkmcnt(7)
	v_mfma_f32_32x32x16_bf16 v[18:33], v[142:145], v[146:149], v[18:33]
	ds_read_b128 v[142:145], v241 offset:61440
	v_exp_f32_e32 v128, v128
	v_exp_f32_e32 v129, v129
	v_add_f32_e32 v247, v128, v247
	v_add_f32_e32 v247, v129, v247
	s_waitcnt lgkmcnt(7)
	v_mfma_f32_32x32x16_bf16 v[2:17], v[200:203], v[150:153], v[2:17]
	ds_read_b128 v[200:203], v242 offset:49152
	v_cvt_pk_bf16_f32 v114, v114, v115
	v_cvt_pk_bf16_f32 v115, v116, v117
	s_waitcnt lgkmcnt(7)
	v_mfma_f32_32x32x16_bf16 v[50:65], v[204:207], v[150:153], v[50:65]
	ds_read_b128 v[204:207], v242 offset:53248
	v_cvt_pk_bf16_f32 v116, v118, v119
	v_cvt_pk_bf16_f32 v117, v120, v121
	s_waitcnt lgkmcnt(7)
	v_mfma_f32_32x32x16_bf16 v[34:49], v[208:211], v[150:153], v[34:49]
	ds_read_b128 v[208:211], v242 offset:57344
	v_cvt_pk_bf16_f32 v118, v122, v123
	v_cvt_pk_bf16_f32 v119, v124, v125
	s_waitcnt lgkmcnt(7)
	v_mfma_f32_32x32x16_bf16 v[18:33], v[212:215], v[150:153], v[18:33]
	ds_read_b128 v[212:215], v242 offset:61440
	v_cvt_pk_bf16_f32 v120, v126, v127
	v_cvt_pk_bf16_f32 v121, v128, v129
	v_add_f32_e32 v238, v238, v247
	v_max_i32_e32 v192, v98, v66
	ds_bpermute_b32 v193, v222, v192
	s_add_i32 s22, s22, 2
	s_mov_b64 s[2:3], 0x100
	v_lshl_add_u64 v[180:181], v[180:181], 0, s[88:89]
	v_lshl_add_u64 v[182:183], v[182:183], 0, s[2:3]
	v_lshl_add_u64 v[184:185], v[184:185], 0, s[2:3]
	s_add_i32 s4, s22, -3
	s_cmp_ge_u32 s4, s21
	s_waitcnt vmcnt(0) lgkmcnt(0)
	v_max_i32_e32 v243, v192, v193
	s_barrier
	s_cbranch_scc0 .LBB0_1097
	v_mfma_f32_32x32x16_bf16 v[2:17], v[130:133], v[114:117], v[2:17]
	v_mfma_f32_32x32x16_bf16 v[50:65], v[134:137], v[114:117], v[50:65]
	v_mfma_f32_32x32x16_bf16 v[34:49], v[138:141], v[114:117], v[34:49]
	v_mfma_f32_32x32x16_bf16 v[18:33], v[142:145], v[114:117], v[18:33]
	v_mfma_f32_32x32x16_bf16 v[2:17], v[200:203], v[118:121], v[2:17]
	v_mfma_f32_32x32x16_bf16 v[50:65], v[204:207], v[118:121], v[50:65]
	v_mfma_f32_32x32x16_bf16 v[34:49], v[208:211], v[118:121], v[34:49]
	v_mfma_f32_32x32x16_bf16 v[18:33], v[212:215], v[118:121], v[18:33]
	s_nop 15
